# memattn Q-fragment loads after the K-staging barrier for waves 0-3 (instead of waves 4-7): same out-of-phase sweeps, other wave half late
# baseline (speedup 1.0000x reference)
.LBB0_123:
	s_add_i32 s4, s5, s6
	s_ashr_i32 s5, s4, 31
	s_lshr_b32 s5, s5, 29
	s_add_i32 s5, s4, s5
	s_ashr_i32 s6, s5, 3
	s_lshl_b32 s6, s6, 1
	s_sub_i32 s7, 64, s6
	s_min_i32 s7, s7, 2
	s_abs_i32 s9, s7
	v_cvt_f32_u32_e32 v0, s9
	s_sub_i32 s10, 0, s9
	s_and_b32 s5, s5, -8
	s_sub_i32 s5, s4, s5
	v_rcp_iflag_f32_e32 v0, v0
	s_abs_i32 s8, s5
	s_xor_b32 s4, s5, s7
	s_ashr_i32 s4, s4, 31
	v_mul_f32_e32 v0, 0x4f7ffffe, v0
	v_cvt_u32_f32_e32 v0, v0
	v_mov_b32_e32 v8, v245
	v_cmp_lt_i32_e32 vcc, v234, v228
	v_readfirstlane_b32 s11, v0
	s_mul_i32 s10, s10, s11
	s_mul_hi_u32 s10, s11, s10
	s_add_i32 s11, s11, s10
	s_mul_hi_u32 s10, s8, s11
	s_mul_i32 s11, s10, s9
	s_sub_i32 s8, s8, s11
	s_add_i32 s11, s10, 1
	s_sub_i32 s12, s8, s9
	s_cmp_ge_u32 s8, s9
	s_cselect_b32 s10, s11, s10
	s_cselect_b32 s8, s12, s8
	s_add_i32 s11, s10, 1
	s_cmp_ge_u32 s8, s9
	s_cselect_b32 s8, s11, s10
	s_xor_b32 s8, s8, s4
	s_sub_i32 s4, s8, s4
	s_mul_i32 s7, s4, s7
	s_sub_i32 s5, s5, s7
	s_add_i32 s5, s6, s5
	s_ashr_i32 s6, s5, 31
	s_lshr_b32 s6, s6, 28
	s_add_i32 s6, s5, s6
	s_ashr_i32 s30, s6, 4
	s_and_b32 s6, s6, 0xfffff0
	s_sub_i32 s5, s5, s6
	s_lshl_b32 s10, s30, 8
	s_lshl_b32 s7, s5, 8
	s_ashr_i32 s11, s10, 31
	s_ashr_i32 s31, s30, 31
	s_ashr_i32 s8, s7, 31
	s_lshl_b64 s[10:11], s[10:11], 12
	s_add_u32 s6, s33, s10
	s_waitcnt lgkmcnt(0)
	v_ashrrev_i32_e32 v2, 6, v8
	s_addc_u32 s9, s40, s11
	s_lshl_b32 s4, s4, 8
	v_bfe_u32 v72, v8, 5, 1
	v_lshlrev_b32_e32 v0, 5, v2
	s_ashr_i32 s5, s4, 31
	s_lshl_b64 s[28:29], s[4:5], 1
	v_readfirstlane_b32 s4, v2
	v_or_b32_e32 v2, v0, v72
	v_and_b32_e32 v9, 31, v8
	v_lshrrev_b32_e32 v10, 5, v8
	s_add_u32 s36, s6, s28
	v_ashrrev_i32_e32 v3, 31, v2
	s_addc_u32 s37, s9, s29
	v_lshlrev_b64 v[4:5], 12, v[2:3]
	v_bitop3_b32 v3, v10, v9, 1 bitop3:0x6c
	v_lshl_add_u64 v[4:5], s[36:37], 0, v[4:5]
	v_lshlrev_b32_e32 v96, 4, v3
	v_lshl_add_u64 v[4:5], v[4:5], 0, v[96:97]
	s_lshl_b32 s9, s4, 14
	s_add_i32 s4, s9, 0
	s_mov_b32 s5, m0
	s_mov_b32 m0, s4
	s_nop 0
	global_load_lds_dwordx4 v[4:5], off
	s_mov_b32 m0, s5
	v_or_b32_e32 v4, 2, v2
	v_ashrrev_i32_e32 v5, 31, v4
	v_lshlrev_b64 v[6:7], 12, v[4:5]
	v_bitop3_b32 v3, v4, v9, 3 bitop3:0x6c
	v_lshl_add_u64 v[6:7], s[36:37], 0, v[6:7]
	v_lshlrev_b32_e32 v4, 4, v3
	v_mov_b32_e32 v5, v97
	v_lshl_add_u64 v[4:5], v[6:7], 0, v[4:5]
	s_add_i32 s5, 0, 0x400
	s_add_i32 s4, s9, s5
	s_mov_b32 s6, m0
	s_mov_b32 m0, s4
	s_nop 0
	global_load_lds_dwordx4 v[4:5], off
	s_mov_b32 m0, s6
	v_or_b32_e32 v4, 4, v2
	v_ashrrev_i32_e32 v5, 31, v4
	v_lshlrev_b64 v[6:7], 12, v[4:5]
	v_bitop3_b32 v3, v4, v9, 5 bitop3:0x6c
	v_lshl_add_u64 v[6:7], s[36:37], 0, v[6:7]
	v_lshlrev_b32_e32 v4, 4, v3
	v_mov_b32_e32 v5, v97
	v_lshl_add_u64 v[4:5], v[6:7], 0, v[4:5]
	s_add_i32 s6, 0, 0x800
	s_add_i32 s4, s9, s6
	s_mov_b32 s10, m0
	s_mov_b32 m0, s4
	s_nop 0
	global_load_lds_dwordx4 v[4:5], off
	s_mov_b32 m0, s10
	v_or_b32_e32 v4, 6, v2
	v_ashrrev_i32_e32 v5, 31, v4
	v_lshlrev_b64 v[6:7], 12, v[4:5]
	v_bitop3_b32 v3, v4, v9, 7 bitop3:0x6c
	v_lshl_add_u64 v[6:7], s[36:37], 0, v[6:7]
	v_lshlrev_b32_e32 v4, 4, v3
	v_mov_b32_e32 v5, v97
	v_lshl_add_u64 v[4:5], v[6:7], 0, v[4:5]
	s_add_i32 s4, s9, s18
	s_mov_b32 s10, m0
	s_mov_b32 m0, s4
	s_nop 0
	global_load_lds_dwordx4 v[4:5], off
	s_mov_b32 m0, s10
	v_or_b32_e32 v4, 8, v2
	v_ashrrev_i32_e32 v5, 31, v4
	v_lshlrev_b64 v[6:7], 12, v[4:5]
	v_bitop3_b32 v3, v4, v9, 9 bitop3:0x6c
	v_lshl_add_u64 v[6:7], s[36:37], 0, v[6:7]
	v_lshlrev_b32_e32 v4, 4, v3
	v_mov_b32_e32 v5, v97
	v_lshl_add_u64 v[4:5], v[6:7], 0, v[4:5]
	s_add_i32 s4, 0, 0x1000
	s_add_i32 s10, s9, s4
	s_mov_b32 s11, m0
	s_mov_b32 m0, s10
	s_nop 0
	global_load_lds_dwordx4 v[4:5], off
	s_mov_b32 m0, s11
	v_or_b32_e32 v4, 10, v2
	v_ashrrev_i32_e32 v5, 31, v4
	v_lshlrev_b64 v[6:7], 12, v[4:5]
	v_bitop3_b32 v3, v4, v9, 11 bitop3:0x6c
	v_lshl_add_u64 v[6:7], s[36:37], 0, v[6:7]
	v_lshlrev_b32_e32 v4, 4, v3
	v_mov_b32_e32 v5, v97
	v_lshl_add_u64 v[4:5], v[6:7], 0, v[4:5]
	s_add_i32 s10, s9, s19
	s_mov_b32 s11, m0
	s_mov_b32 m0, s10
	s_nop 0
	global_load_lds_dwordx4 v[4:5], off
	s_mov_b32 m0, s11
	v_or_b32_e32 v4, 12, v2
	v_ashrrev_i32_e32 v5, 31, v4
	v_lshlrev_b64 v[6:7], 12, v[4:5]
	v_bitop3_b32 v3, v4, v9, 13 bitop3:0x6c
	v_lshl_add_u64 v[6:7], s[36:37], 0, v[6:7]
	v_lshlrev_b32_e32 v4, 4, v3
	v_mov_b32_e32 v5, v97
	v_lshl_add_u64 v[4:5], v[6:7], 0, v[4:5]
	s_add_i32 s10, s9, s41
	s_mov_b32 s11, m0
	s_mov_b32 m0, s10
	s_nop 0
	global_load_lds_dwordx4 v[4:5], off
	s_mov_b32 m0, s11
	v_or_b32_e32 v4, 14, v2
	v_ashrrev_i32_e32 v5, 31, v4
	v_lshlrev_b64 v[6:7], 12, v[4:5]
	v_bitop3_b32 v3, v4, v9, 15 bitop3:0x6c
	v_lshl_add_u64 v[6:7], s[36:37], 0, v[6:7]
	v_lshlrev_b32_e32 v4, 4, v3
	v_mov_b32_e32 v5, v97
	v_lshl_add_u64 v[4:5], v[6:7], 0, v[4:5]
	s_add_i32 s10, s9, s42
	s_mov_b32 s11, m0
	s_mov_b32 m0, s10
	s_nop 0
	global_load_lds_dwordx4 v[4:5], off
	s_mov_b32 m0, s11
	v_or_b32_e32 v4, 16, v2
	v_ashrrev_i32_e32 v5, 31, v4
	v_lshlrev_b64 v[4:5], 12, v[4:5]
	v_lshl_add_u64 v[4:5], s[36:37], 0, v[4:5]
	v_lshl_add_u64 v[4:5], v[4:5], 0, v[96:97]
	s_add_i32 s10, s9, s43
	s_mov_b32 s11, m0
	s_mov_b32 m0, s10
	s_nop 0
	global_load_lds_dwordx4 v[4:5], off
	s_mov_b32 m0, s11
	v_or_b32_e32 v4, 18, v2
	v_ashrrev_i32_e32 v5, 31, v4
	v_lshlrev_b64 v[6:7], 12, v[4:5]
	v_bitop3_b32 v3, v4, v9, 3 bitop3:0x6c
	v_lshl_add_u64 v[6:7], s[36:37], 0, v[6:7]
	v_lshlrev_b32_e32 v96, 4, v3
	v_lshl_add_u64 v[4:5], v[6:7], 0, v[96:97]
	s_add_i32 s10, s9, s44
	s_mov_b32 s11, m0
	s_mov_b32 m0, s10
	s_nop 0
	global_load_lds_dwordx4 v[4:5], off
	s_mov_b32 m0, s11
	v_or_b32_e32 v4, 20, v2
	v_ashrrev_i32_e32 v5, 31, v4
	v_lshlrev_b64 v[6:7], 12, v[4:5]
	v_bitop3_b32 v3, v4, v9, 5 bitop3:0x6c
	v_lshl_add_u64 v[6:7], s[36:37], 0, v[6:7]
	v_lshlrev_b32_e32 v96, 4, v3
	v_lshl_add_u64 v[4:5], v[6:7], 0, v[96:97]
	s_add_i32 s10, s9, s45
	s_mov_b32 s11, m0
	s_mov_b32 m0, s10
	s_nop 0
	global_load_lds_dwordx4 v[4:5], off
	s_mov_b32 m0, s11
	v_or_b32_e32 v4, 22, v2
	v_ashrrev_i32_e32 v5, 31, v4
	v_lshlrev_b64 v[6:7], 12, v[4:5]
	v_bitop3_b32 v3, v4, v9, 7 bitop3:0x6c
	v_lshl_add_u64 v[6:7], s[36:37], 0, v[6:7]
	v_lshlrev_b32_e32 v96, 4, v3
	v_lshl_add_u64 v[4:5], v[6:7], 0, v[96:97]
	s_add_i32 s10, s9, s46
	s_mov_b32 s11, m0
	s_mov_b32 m0, s10
	s_nop 0
	global_load_lds_dwordx4 v[4:5], off
	s_mov_b32 m0, s11
	v_or_b32_e32 v4, 24, v2
	v_ashrrev_i32_e32 v5, 31, v4
	v_lshlrev_b64 v[6:7], 12, v[4:5]
	v_bitop3_b32 v3, v4, v9, 9 bitop3:0x6c
	v_lshl_add_u64 v[6:7], s[36:37], 0, v[6:7]
	v_lshlrev_b32_e32 v96, 4, v3
	v_lshl_add_u64 v[4:5], v[6:7], 0, v[96:97]
	s_add_i32 s10, s9, s47
	s_mov_b32 s11, m0
	s_mov_b32 m0, s10
	s_nop 0
	global_load_lds_dwordx4 v[4:5], off
	s_mov_b32 m0, s11
	v_or_b32_e32 v4, 26, v2
	v_ashrrev_i32_e32 v5, 31, v4
	v_lshlrev_b64 v[6:7], 12, v[4:5]
	v_bitop3_b32 v3, v4, v9, 11 bitop3:0x6c
	v_lshl_add_u64 v[6:7], s[36:37], 0, v[6:7]
	v_lshlrev_b32_e32 v96, 4, v3
	v_lshl_add_u64 v[4:5], v[6:7], 0, v[96:97]
	s_add_i32 s10, s9, s48
	s_mov_b32 s11, m0
	s_mov_b32 m0, s10
	s_nop 0
	global_load_lds_dwordx4 v[4:5], off
	s_mov_b32 m0, s11
	v_or_b32_e32 v4, 28, v2
	v_ashrrev_i32_e32 v5, 31, v4
	v_lshlrev_b64 v[6:7], 12, v[4:5]
	v_bitop3_b32 v3, v4, v9, 13 bitop3:0x6c
	v_lshl_add_u64 v[6:7], s[36:37], 0, v[6:7]
	v_lshlrev_b32_e32 v96, 4, v3
	v_or_b32_e32 v2, 30, v2
	v_lshl_add_u64 v[4:5], v[6:7], 0, v[96:97]
	v_ashrrev_i32_e32 v3, 31, v2
	s_add_i32 s10, s9, s49
	s_mov_b32 s11, m0
	s_mov_b32 m0, s10
	s_nop 0
	global_load_lds_dwordx4 v[4:5], off
	s_mov_b32 m0, s11
	v_lshlrev_b64 v[4:5], 12, v[2:3]
	v_bitop3_b32 v2, v2, v9, 15 bitop3:0x6c
	v_lshl_add_u64 v[4:5], s[36:37], 0, v[4:5]
	v_lshlrev_b32_e32 v96, 4, v2
	v_lshl_add_u64 v[2:3], v[4:5], 0, v[96:97]
	s_add_i32 s9, s9, s50
	s_mov_b32 s10, m0
	s_mov_b32 m0, s9
	s_nop 0
	global_load_lds_dwordx4 v[2:3], off
	s_mov_b32 m0, s10
	s_lshl_b64 s[10:11], s[30:31], 12
	s_add_u32 s38, s10, s7
	v_ashrrev_i32_e32 v1, 31, v0
	s_addc_u32 s39, s11, s8
	v_lshl_add_u64 v[0:1], s[38:39], 0, v[0:1]
	v_or_b32_e32 v0, v0, v9
	v_lshlrev_b64 v[0:1], 11, v[0:1]
	v_lshl_add_u64 v[0:1], s[24:25], 0, v[0:1]
	v_lshl_add_u64 v[0:1], v[0:1], 0, s[28:29]
	v_lshlrev_b32_e32 v96, 4, v72
	v_lshl_add_u64 v[0:1], v[0:1], 0, v[96:97]
	v_mov_b32_e32 v184, v0
	v_mov_b32_e32 v185, v1
	s_bitcmp0_b32 s9, 16
	s_cbranch_scc1 .Lma_q_late
	global_load_dwordx4 v[142:145], v[0:1], off
	global_load_dwordx4 v[138:141], v[0:1], off offset:32
	global_load_dwordx4 v[134:137], v[0:1], off offset:64
	global_load_dwordx4 v[130:133], v[0:1], off offset:96
	global_load_dwordx4 v[126:129], v[0:1], off offset:128
	global_load_dwordx4 v[122:125], v[0:1], off offset:160
	global_load_dwordx4 v[118:121], v[0:1], off offset:192
	global_load_dwordx4 v[114:117], v[0:1], off offset:224
	global_load_dwordx4 v[60:63], v[0:1], off offset:256
	global_load_dwordx4 v[56:59], v[0:1], off offset:288
	global_load_dwordx4 v[52:55], v[0:1], off offset:320
	global_load_dwordx4 v[48:51], v[0:1], off offset:352
	global_load_dwordx4 v[44:47], v[0:1], off offset:384
	global_load_dwordx4 v[40:43], v[0:1], off offset:416
	global_load_dwordx4 v[36:39], v[0:1], off offset:448
	global_load_dwordx4 v[32:35], v[0:1], off offset:480
.Lma_q_late:
	v_and_b32_e32 v73, 15, v8
	v_bitop3_b32 v0, v10, v73, 1 bitop3:0x6c
	v_lshl_add_u32 v162, v9, 9, 0
	v_lshlrev_b32_e32 v161, 4, v0
	v_add_u32_e32 v89, v162, v161
	s_waitcnt vmcnt(0)
	s_barrier
	s_bitcmp1_b32 s9, 16
	s_cbranch_scc1 .Lma_q_done
	global_load_dwordx4 v[142:145], v[184:185], off
	global_load_dwordx4 v[138:141], v[184:185], off offset:32
	global_load_dwordx4 v[134:137], v[184:185], off offset:64
	global_load_dwordx4 v[130:133], v[184:185], off offset:96
	global_load_dwordx4 v[126:129], v[184:185], off offset:128
	global_load_dwordx4 v[122:125], v[184:185], off offset:160
	global_load_dwordx4 v[118:121], v[184:185], off offset:192
	global_load_dwordx4 v[114:117], v[184:185], off offset:224
	global_load_dwordx4 v[60:63], v[184:185], off offset:256
	global_load_dwordx4 v[56:59], v[184:185], off offset:288
	global_load_dwordx4 v[52:55], v[184:185], off offset:320
	global_load_dwordx4 v[48:51], v[184:185], off offset:352
	global_load_dwordx4 v[44:47], v[184:185], off offset:384
	global_load_dwordx4 v[40:43], v[184:185], off offset:416
	global_load_dwordx4 v[36:39], v[184:185], off offset:448
	global_load_dwordx4 v[32:35], v[184:185], off offset:480
